# m21 + index level-2 histogram pass: one four-key threshold-bin test (4 xor, min3, min, cmp, branch) in front of each K[jj] group instead of nine instructions per key
# baseline (speedup 1.0000x reference)
.LBB0_1397:
	s_mov_b32 s68, s69
	s_mov_b32 s70, s69
	s_mov_b32 s71, s69
	v_mov_b64_e32 v[6:7], s[68:69]
	v_add_u32_e32 v3, s66, v39
	v_mov_b64_e32 v[8:9], s[70:71]
	v_lshlrev_b32_e32 v4, 4, v167
	v_readlane_b32 s0, v251, 31
	ds_write_b128 v3, v[6:9]
	ds_write_b128 v3, v[6:9] offset:1024
	ds_write_b128 v3, v[6:9] offset:2048
	ds_write_b128 v3, v[6:9] offset:3072
	ds_write_b128 v3, v[6:9] offset:4096
	ds_write_b128 v3, v[6:9] offset:5120
	ds_write_b128 v3, v[6:9] offset:6144
	ds_write_b128 v3, v[6:9] offset:7168
	ds_write_b128 v3, v[6:9] offset:8192
	ds_write_b128 v3, v[6:9] offset:9216
	ds_write_b128 v3, v[6:9] offset:10240
	ds_write_b128 v3, v[6:9] offset:11264
	ds_write_b128 v3, v[6:9] offset:12288
	ds_write_b128 v3, v[6:9] offset:13312
	ds_write_b128 v3, v[6:9] offset:14336
	ds_write_b128 v3, v[6:9] offset:15360
	v_add_u32_e32 v6, s0, v4
	s_waitcnt lgkmcnt(0)
	s_barrier
	ds_read_b32 v7, v6 offset:8
	s_waitcnt lgkmcnt(0)
	v_cmp_ne_u32_e32 vcc, 0, v7
	s_and_saveexec_b64 s[42:43], vcc
	s_cbranch_execz .LBB0_1717
	ds_read_b32 v6, v6
	s_waitcnt lgkmcnt(0)
	v_lshlrev_b32_e32 v12, 21, v6
	s_and_b64 vcc, exec, s[78:79]
	s_cbranch_vccz .LBB0_1408
	v_xor_b32_e32 v7, v12, v171
	v_xor_b32_e32 v8, v12, v170
	v_xor_b32_e32 v9, v12, v169
	v_xor_b32_e32 v10, v12, v168
	v_min3_u32 v7, v7, v8, v9
	v_min_u32_e32 v7, v7, v10
	v_cmp_gt_u32_e32 vcc, 0x200000, v7
	s_cbranch_vccz .Ll2s_1
	v_lshrrev_b32_e32 v7, 21, v171
	s_waitcnt lgkmcnt(0)
	v_cmp_eq_u32_e32 vcc, v7, v6
	s_and_saveexec_b64 s[0:1], vcc
	v_lshrrev_b32_e32 v7, 13, v171
	v_bfe_u32 v8, v171, 10, 11
	v_bitop3_b32 v7, v7, v8, 28 bitop3:0x6c
	v_lshl_add_u32 v7, v7, 2, v40
	ds_add_u32 v7, v186
	s_or_b64 exec, exec, s[0:1]
	v_lshrrev_b32_e32 v7, 21, v170
	v_cmp_eq_u32_e32 vcc, v7, v6
	s_and_saveexec_b64 s[0:1], vcc
	v_lshrrev_b32_e32 v7, 13, v170
	v_bfe_u32 v8, v170, 10, 11
	v_bitop3_b32 v7, v7, v8, 28 bitop3:0x6c
	v_lshl_add_u32 v7, v7, 2, v40
	ds_add_u32 v7, v186
	s_or_b64 exec, exec, s[0:1]
	v_lshrrev_b32_e32 v7, 21, v169
	v_cmp_eq_u32_e32 vcc, v7, v6
	s_and_saveexec_b64 s[0:1], vcc
	v_lshrrev_b32_e32 v7, 13, v169
	v_bfe_u32 v8, v169, 10, 11
	v_bitop3_b32 v7, v7, v8, 28 bitop3:0x6c
	v_lshl_add_u32 v7, v7, 2, v40
	ds_add_u32 v7, v186
	s_or_b64 exec, exec, s[0:1]
	v_lshrrev_b32_e32 v7, 21, v168
	v_cmp_eq_u32_e32 vcc, v7, v6
	s_and_saveexec_b64 s[0:1], vcc
	v_lshrrev_b32_e32 v7, 13, v168
	v_bfe_u32 v8, v168, 10, 11
	v_bitop3_b32 v7, v7, v8, 28 bitop3:0x6c
	v_lshl_add_u32 v7, v7, 2, v40
	ds_add_u32 v7, v186
	s_or_b64 exec, exec, s[0:1]
.Ll2s_1:
.LBB0_1408:
	s_cmp_lt_i32 s77, 8
	s_cbranch_scc1 .LBB0_1559
	v_xor_b32_e32 v7, v12, v166
	v_xor_b32_e32 v8, v12, v165
	v_xor_b32_e32 v9, v12, v164
	v_xor_b32_e32 v10, v12, v163
	v_min3_u32 v7, v7, v8, v9
	v_min_u32_e32 v7, v7, v10
	v_cmp_gt_u32_e32 vcc, 0x200000, v7
	s_cbranch_vccz .Ll2s_2
	v_lshrrev_b32_e32 v7, 21, v166
	s_waitcnt lgkmcnt(0)
	v_cmp_eq_u32_e32 vcc, v7, v6
	s_and_saveexec_b64 s[0:1], vcc
	v_lshrrev_b32_e32 v7, 13, v166
	v_bfe_u32 v8, v166, 10, 11
	v_bitop3_b32 v7, v7, v8, 28 bitop3:0x6c
	v_lshl_add_u32 v7, v7, 2, v40
	ds_add_u32 v7, v186
	s_or_b64 exec, exec, s[0:1]
	v_lshrrev_b32_e32 v7, 21, v165
	v_cmp_eq_u32_e32 vcc, v7, v6
	s_and_saveexec_b64 s[0:1], vcc
	v_lshrrev_b32_e32 v7, 13, v165
	v_bfe_u32 v8, v165, 10, 11
	v_bitop3_b32 v7, v7, v8, 28 bitop3:0x6c
	v_lshl_add_u32 v7, v7, 2, v40
	ds_add_u32 v7, v186
	s_or_b64 exec, exec, s[0:1]
	v_lshrrev_b32_e32 v7, 21, v164
	v_cmp_eq_u32_e32 vcc, v7, v6
	s_and_saveexec_b64 s[0:1], vcc
	v_lshrrev_b32_e32 v7, 13, v164
	v_bfe_u32 v8, v164, 10, 11
	v_bitop3_b32 v7, v7, v8, 28 bitop3:0x6c
	v_lshl_add_u32 v7, v7, 2, v40
	ds_add_u32 v7, v186
	s_or_b64 exec, exec, s[0:1]
	v_lshrrev_b32_e32 v7, 21, v163
	v_cmp_eq_u32_e32 vcc, v7, v6
	s_and_saveexec_b64 s[0:1], vcc
	v_lshrrev_b32_e32 v7, 13, v163
	v_bfe_u32 v8, v163, 10, 11
	v_bitop3_b32 v7, v7, v8, 28 bitop3:0x6c
	v_lshl_add_u32 v7, v7, 2, v40
	ds_add_u32 v7, v186
	s_or_b64 exec, exec, s[0:1]
.Ll2s_2:
	s_cmp_lt_i32 s77, 16
	s_cbranch_scc0 .LBB0_1560

.LBB0_1419:
	v_xor_b32_e32 v7, v12, v158
	v_xor_b32_e32 v8, v12, v157
	v_xor_b32_e32 v9, v12, v156
	v_xor_b32_e32 v10, v12, v155
	v_min3_u32 v7, v7, v8, v9
	v_min_u32_e32 v7, v7, v10
	v_cmp_gt_u32_e32 vcc, 0x200000, v7
	s_cbranch_vccz .Ll2s_3
	v_lshrrev_b32_e32 v7, 21, v158
	s_waitcnt lgkmcnt(0)
	v_cmp_eq_u32_e32 vcc, v7, v6
	s_and_saveexec_b64 s[0:1], vcc
	v_lshrrev_b32_e32 v7, 13, v158
	v_bfe_u32 v8, v158, 10, 11
	v_bitop3_b32 v7, v7, v8, 28 bitop3:0x6c
	v_lshl_add_u32 v7, v7, 2, v40
	ds_add_u32 v7, v186
	s_or_b64 exec, exec, s[0:1]
	v_lshrrev_b32_e32 v7, 21, v157
	v_cmp_eq_u32_e32 vcc, v7, v6
	s_and_saveexec_b64 s[0:1], vcc
	v_lshrrev_b32_e32 v7, 13, v157
	v_bfe_u32 v8, v157, 10, 11
	v_bitop3_b32 v7, v7, v8, 28 bitop3:0x6c
	v_lshl_add_u32 v7, v7, 2, v40
	ds_add_u32 v7, v186
	s_or_b64 exec, exec, s[0:1]
	v_lshrrev_b32_e32 v7, 21, v156
	v_cmp_eq_u32_e32 vcc, v7, v6
	s_and_saveexec_b64 s[0:1], vcc
	v_lshrrev_b32_e32 v7, 13, v156
	v_bfe_u32 v8, v156, 10, 11
	v_bitop3_b32 v7, v7, v8, 28 bitop3:0x6c
	v_lshl_add_u32 v7, v7, 2, v40
	ds_add_u32 v7, v186
	s_or_b64 exec, exec, s[0:1]
	v_lshrrev_b32_e32 v7, 21, v155
	v_cmp_eq_u32_e32 vcc, v7, v6
	s_and_saveexec_b64 s[0:1], vcc
	v_lshrrev_b32_e32 v7, 13, v155
	v_bfe_u32 v8, v155, 10, 11
	v_bitop3_b32 v7, v7, v8, 28 bitop3:0x6c
	v_lshl_add_u32 v7, v7, 2, v40
	ds_add_u32 v7, v186
	s_or_b64 exec, exec, s[0:1]
.Ll2s_3:
	s_cmp_lt_i32 s77, 32
	s_cbranch_scc0 .LBB0_1570

.LBB0_1429:
	v_xor_b32_e32 v7, v12, v150
	v_xor_b32_e32 v8, v12, v149
	v_xor_b32_e32 v9, v12, v148
	v_xor_b32_e32 v10, v12, v147
	v_min3_u32 v7, v7, v8, v9
	v_min_u32_e32 v7, v7, v10
	v_cmp_gt_u32_e32 vcc, 0x200000, v7
	s_cbranch_vccz .Ll2s_4
	v_lshrrev_b32_e32 v7, 21, v150
	s_waitcnt lgkmcnt(0)
	v_cmp_eq_u32_e32 vcc, v7, v6
	s_and_saveexec_b64 s[0:1], vcc
	v_lshrrev_b32_e32 v7, 13, v150
	v_bfe_u32 v8, v150, 10, 11
	v_bitop3_b32 v7, v7, v8, 28 bitop3:0x6c
	v_lshl_add_u32 v7, v7, 2, v40
	ds_add_u32 v7, v186
	s_or_b64 exec, exec, s[0:1]
	v_lshrrev_b32_e32 v7, 21, v149
	v_cmp_eq_u32_e32 vcc, v7, v6
	s_and_saveexec_b64 s[0:1], vcc
	v_lshrrev_b32_e32 v7, 13, v149
	v_bfe_u32 v8, v149, 10, 11
	v_bitop3_b32 v7, v7, v8, 28 bitop3:0x6c
	v_lshl_add_u32 v7, v7, 2, v40
	ds_add_u32 v7, v186
	s_or_b64 exec, exec, s[0:1]
	v_lshrrev_b32_e32 v7, 21, v148
	v_cmp_eq_u32_e32 vcc, v7, v6
	s_and_saveexec_b64 s[0:1], vcc
	v_lshrrev_b32_e32 v7, 13, v148
	v_bfe_u32 v8, v148, 10, 11
	v_bitop3_b32 v7, v7, v8, 28 bitop3:0x6c
	v_lshl_add_u32 v7, v7, 2, v40
	ds_add_u32 v7, v186
	s_or_b64 exec, exec, s[0:1]
	v_lshrrev_b32_e32 v7, 21, v147
	v_cmp_eq_u32_e32 vcc, v7, v6
	s_and_saveexec_b64 s[0:1], vcc
	v_lshrrev_b32_e32 v7, 13, v147
	v_bfe_u32 v8, v147, 10, 11
	v_bitop3_b32 v7, v7, v8, 28 bitop3:0x6c
	v_lshl_add_u32 v7, v7, 2, v40
	ds_add_u32 v7, v186
	s_or_b64 exec, exec, s[0:1]
.Ll2s_4:
	s_cmp_lt_i32 s77, 48
	s_cbranch_scc0 .LBB0_1580

.LBB0_1439:
	v_xor_b32_e32 v7, v12, v142
	v_xor_b32_e32 v8, v12, v141
	v_xor_b32_e32 v9, v12, v140
	v_xor_b32_e32 v10, v12, v139
	v_min3_u32 v7, v7, v8, v9
	v_min_u32_e32 v7, v7, v10
	v_cmp_gt_u32_e32 vcc, 0x200000, v7
	s_cbranch_vccz .Ll2s_5
	v_lshrrev_b32_e32 v7, 21, v142
	s_waitcnt lgkmcnt(0)
	v_cmp_eq_u32_e32 vcc, v7, v6
	s_and_saveexec_b64 s[0:1], vcc
	v_lshrrev_b32_e32 v7, 13, v142
	v_bfe_u32 v8, v142, 10, 11
	v_bitop3_b32 v7, v7, v8, 28 bitop3:0x6c
	v_lshl_add_u32 v7, v7, 2, v40
	ds_add_u32 v7, v186
	s_or_b64 exec, exec, s[0:1]
	v_lshrrev_b32_e32 v7, 21, v141
	v_cmp_eq_u32_e32 vcc, v7, v6
	s_and_saveexec_b64 s[0:1], vcc
	v_lshrrev_b32_e32 v7, 13, v141
	v_bfe_u32 v8, v141, 10, 11
	v_bitop3_b32 v7, v7, v8, 28 bitop3:0x6c
	v_lshl_add_u32 v7, v7, 2, v40
	ds_add_u32 v7, v186
	s_or_b64 exec, exec, s[0:1]
	v_lshrrev_b32_e32 v7, 21, v140
	v_cmp_eq_u32_e32 vcc, v7, v6
	s_and_saveexec_b64 s[0:1], vcc
	v_lshrrev_b32_e32 v7, 13, v140
	v_bfe_u32 v8, v140, 10, 11
	v_bitop3_b32 v7, v7, v8, 28 bitop3:0x6c
	v_lshl_add_u32 v7, v7, 2, v40
	ds_add_u32 v7, v186
	s_or_b64 exec, exec, s[0:1]
	v_lshrrev_b32_e32 v7, 21, v139
	v_cmp_eq_u32_e32 vcc, v7, v6
	s_and_saveexec_b64 s[0:1], vcc
	v_lshrrev_b32_e32 v7, 13, v139
	v_bfe_u32 v8, v139, 10, 11
	v_bitop3_b32 v7, v7, v8, 28 bitop3:0x6c
	v_lshl_add_u32 v7, v7, 2, v40
	ds_add_u32 v7, v186
	s_or_b64 exec, exec, s[0:1]
.Ll2s_5:
	s_cmp_lt_i32 s77, 64
	s_cbranch_scc0 .LBB0_1590

.LBB0_1449:
	v_xor_b32_e32 v7, v12, v134
	v_xor_b32_e32 v8, v12, v133
	v_xor_b32_e32 v9, v12, v132
	v_xor_b32_e32 v10, v12, v131
	v_min3_u32 v7, v7, v8, v9
	v_min_u32_e32 v7, v7, v10
	v_cmp_gt_u32_e32 vcc, 0x200000, v7
	s_cbranch_vccz .Ll2s_6
	v_lshrrev_b32_e32 v7, 21, v134
	s_waitcnt lgkmcnt(0)
	v_cmp_eq_u32_e32 vcc, v7, v6
	s_and_saveexec_b64 s[0:1], vcc
	v_lshrrev_b32_e32 v7, 13, v134
	v_bfe_u32 v8, v134, 10, 11
	v_bitop3_b32 v7, v7, v8, 28 bitop3:0x6c
	v_lshl_add_u32 v7, v7, 2, v40
	ds_add_u32 v7, v186
	s_or_b64 exec, exec, s[0:1]
	v_lshrrev_b32_e32 v7, 21, v133
	v_cmp_eq_u32_e32 vcc, v7, v6
	s_and_saveexec_b64 s[0:1], vcc
	v_lshrrev_b32_e32 v7, 13, v133
	v_bfe_u32 v8, v133, 10, 11
	v_bitop3_b32 v7, v7, v8, 28 bitop3:0x6c
	v_lshl_add_u32 v7, v7, 2, v40
	ds_add_u32 v7, v186
	s_or_b64 exec, exec, s[0:1]
	v_lshrrev_b32_e32 v7, 21, v132
	v_cmp_eq_u32_e32 vcc, v7, v6
	s_and_saveexec_b64 s[0:1], vcc
	v_lshrrev_b32_e32 v7, 13, v132
	v_bfe_u32 v8, v132, 10, 11
	v_bitop3_b32 v7, v7, v8, 28 bitop3:0x6c
	v_lshl_add_u32 v7, v7, 2, v40
	ds_add_u32 v7, v186
	s_or_b64 exec, exec, s[0:1]
	v_lshrrev_b32_e32 v7, 21, v131
	v_cmp_eq_u32_e32 vcc, v7, v6
	s_and_saveexec_b64 s[0:1], vcc
	v_lshrrev_b32_e32 v7, 13, v131
	v_bfe_u32 v8, v131, 10, 11
	v_bitop3_b32 v7, v7, v8, 28 bitop3:0x6c
	v_lshl_add_u32 v7, v7, 2, v40
	ds_add_u32 v7, v186
	s_or_b64 exec, exec, s[0:1]
.Ll2s_6:
	s_cmpk_lt_i32 s77, 0x50
	s_cbranch_scc0 .LBB0_1600

.LBB0_1459:
	v_xor_b32_e32 v7, v12, v126
	v_xor_b32_e32 v8, v12, v125
	v_xor_b32_e32 v9, v12, v124
	v_xor_b32_e32 v10, v12, v123
	v_min3_u32 v7, v7, v8, v9
	v_min_u32_e32 v7, v7, v10
	v_cmp_gt_u32_e32 vcc, 0x200000, v7
	s_cbranch_vccz .Ll2s_7
	v_lshrrev_b32_e32 v7, 21, v126
	s_waitcnt lgkmcnt(0)
	v_cmp_eq_u32_e32 vcc, v7, v6
	s_and_saveexec_b64 s[0:1], vcc
	v_lshrrev_b32_e32 v7, 13, v126
	v_bfe_u32 v8, v126, 10, 11
	v_bitop3_b32 v7, v7, v8, 28 bitop3:0x6c
	v_lshl_add_u32 v7, v7, 2, v40
	ds_add_u32 v7, v186
	s_or_b64 exec, exec, s[0:1]
	v_lshrrev_b32_e32 v7, 21, v125
	v_cmp_eq_u32_e32 vcc, v7, v6
	s_and_saveexec_b64 s[0:1], vcc
	v_lshrrev_b32_e32 v7, 13, v125
	v_bfe_u32 v8, v125, 10, 11
	v_bitop3_b32 v7, v7, v8, 28 bitop3:0x6c
	v_lshl_add_u32 v7, v7, 2, v40
	ds_add_u32 v7, v186
	s_or_b64 exec, exec, s[0:1]
	v_lshrrev_b32_e32 v7, 21, v124
	v_cmp_eq_u32_e32 vcc, v7, v6
	s_and_saveexec_b64 s[0:1], vcc
	v_lshrrev_b32_e32 v7, 13, v124
	v_bfe_u32 v8, v124, 10, 11
	v_bitop3_b32 v7, v7, v8, 28 bitop3:0x6c
	v_lshl_add_u32 v7, v7, 2, v40
	ds_add_u32 v7, v186
	s_or_b64 exec, exec, s[0:1]
	v_lshrrev_b32_e32 v7, 21, v123
	v_cmp_eq_u32_e32 vcc, v7, v6
	s_and_saveexec_b64 s[0:1], vcc
	v_lshrrev_b32_e32 v7, 13, v123
	v_bfe_u32 v8, v123, 10, 11
	v_bitop3_b32 v7, v7, v8, 28 bitop3:0x6c
	v_lshl_add_u32 v7, v7, 2, v40
	ds_add_u32 v7, v186
	s_or_b64 exec, exec, s[0:1]
.Ll2s_7:
	s_cmpk_lt_i32 s77, 0x60
	s_cbranch_scc0 .LBB0_1610

.LBB0_1469:
	v_xor_b32_e32 v7, v12, v118
	v_xor_b32_e32 v8, v12, v117
	v_xor_b32_e32 v9, v12, v115
	v_xor_b32_e32 v10, v12, v114
	v_min3_u32 v7, v7, v8, v9
	v_min_u32_e32 v7, v7, v10
	v_cmp_gt_u32_e32 vcc, 0x200000, v7
	s_cbranch_vccz .Ll2s_8
	v_lshrrev_b32_e32 v7, 21, v118
	s_waitcnt lgkmcnt(0)
	v_cmp_eq_u32_e32 vcc, v7, v6
	s_and_saveexec_b64 s[0:1], vcc
	v_lshrrev_b32_e32 v7, 13, v118
	v_bfe_u32 v8, v118, 10, 11
	v_bitop3_b32 v7, v7, v8, 28 bitop3:0x6c
	v_lshl_add_u32 v7, v7, 2, v40
	ds_add_u32 v7, v186
	s_or_b64 exec, exec, s[0:1]
	v_lshrrev_b32_e32 v7, 21, v117
	v_cmp_eq_u32_e32 vcc, v7, v6
	s_and_saveexec_b64 s[0:1], vcc
	v_lshrrev_b32_e32 v7, 13, v117
	v_bfe_u32 v8, v117, 10, 11
	v_bitop3_b32 v7, v7, v8, 28 bitop3:0x6c
	v_lshl_add_u32 v7, v7, 2, v40
	ds_add_u32 v7, v186
	s_or_b64 exec, exec, s[0:1]
	v_lshrrev_b32_e32 v7, 21, v115
	v_cmp_eq_u32_e32 vcc, v7, v6
	s_and_saveexec_b64 s[0:1], vcc
	v_lshrrev_b32_e32 v7, 13, v115
	v_bfe_u32 v8, v115, 10, 11
	v_bitop3_b32 v7, v7, v8, 28 bitop3:0x6c
	v_lshl_add_u32 v7, v7, 2, v40
	ds_add_u32 v7, v186
	s_or_b64 exec, exec, s[0:1]
	v_lshrrev_b32_e32 v7, 21, v114
	v_cmp_eq_u32_e32 vcc, v7, v6
	s_and_saveexec_b64 s[0:1], vcc
	v_lshrrev_b32_e32 v7, 13, v114
	v_bfe_u32 v8, v114, 10, 11
	v_bitop3_b32 v7, v7, v8, 28 bitop3:0x6c
	v_lshl_add_u32 v7, v7, 2, v40
	ds_add_u32 v7, v186
	s_or_b64 exec, exec, s[0:1]
.Ll2s_8:
	s_cmpk_lt_i32 s77, 0x70
	s_cbranch_scc0 .LBB0_1620

.LBB0_1479:
	v_xor_b32_e32 v7, v12, v109
	v_xor_b32_e32 v8, v12, v108
	v_xor_b32_e32 v9, v12, v107
	v_xor_b32_e32 v10, v12, v105
	v_min3_u32 v7, v7, v8, v9
	v_min_u32_e32 v7, v7, v10
	v_cmp_gt_u32_e32 vcc, 0x200000, v7
	s_cbranch_vccz .Ll2s_9
	v_lshrrev_b32_e32 v7, 21, v109
	s_waitcnt lgkmcnt(0)
	v_cmp_eq_u32_e32 vcc, v7, v6
	s_and_saveexec_b64 s[0:1], vcc
	v_lshrrev_b32_e32 v7, 13, v109
	v_bfe_u32 v8, v109, 10, 11
	v_bitop3_b32 v7, v7, v8, 28 bitop3:0x6c
	v_lshl_add_u32 v7, v7, 2, v40
	ds_add_u32 v7, v186
	s_or_b64 exec, exec, s[0:1]
	v_lshrrev_b32_e32 v7, 21, v108
	v_cmp_eq_u32_e32 vcc, v7, v6
	s_and_saveexec_b64 s[0:1], vcc
	v_lshrrev_b32_e32 v7, 13, v108
	v_bfe_u32 v8, v108, 10, 11
	v_bitop3_b32 v7, v7, v8, 28 bitop3:0x6c
	v_lshl_add_u32 v7, v7, 2, v40
	ds_add_u32 v7, v186
	s_or_b64 exec, exec, s[0:1]
	v_lshrrev_b32_e32 v7, 21, v107
	v_cmp_eq_u32_e32 vcc, v7, v6
	s_and_saveexec_b64 s[0:1], vcc
	v_lshrrev_b32_e32 v7, 13, v107
	v_bfe_u32 v8, v107, 10, 11
	v_bitop3_b32 v7, v7, v8, 28 bitop3:0x6c
	v_lshl_add_u32 v7, v7, 2, v40
	ds_add_u32 v7, v186
	s_or_b64 exec, exec, s[0:1]
	v_lshrrev_b32_e32 v7, 21, v105
	v_cmp_eq_u32_e32 vcc, v7, v6
	s_and_saveexec_b64 s[0:1], vcc
	v_lshrrev_b32_e32 v7, 13, v105
	v_bfe_u32 v8, v105, 10, 11
	v_bitop3_b32 v7, v7, v8, 28 bitop3:0x6c
	v_lshl_add_u32 v7, v7, 2, v40
	ds_add_u32 v7, v186
	s_or_b64 exec, exec, s[0:1]
.Ll2s_9:
	s_cmpk_lt_i32 s77, 0x80
	s_cbranch_scc0 .LBB0_1630

.LBB0_1489:
	v_xor_b32_e32 v7, v12, v101
	v_xor_b32_e32 v8, v12, v100
	v_xor_b32_e32 v9, v12, v99
	v_xor_b32_e32 v10, v12, v98
	v_min3_u32 v7, v7, v8, v9
	v_min_u32_e32 v7, v7, v10
	v_cmp_gt_u32_e32 vcc, 0x200000, v7
	s_cbranch_vccz .Ll2s_10
	v_lshrrev_b32_e32 v7, 21, v101
	s_waitcnt lgkmcnt(0)
	v_cmp_eq_u32_e32 vcc, v7, v6
	s_and_saveexec_b64 s[0:1], vcc
	v_lshrrev_b32_e32 v7, 13, v101
	v_bfe_u32 v8, v101, 10, 11
	v_bitop3_b32 v7, v7, v8, 28 bitop3:0x6c
	v_lshl_add_u32 v7, v7, 2, v40
	ds_add_u32 v7, v186
	s_or_b64 exec, exec, s[0:1]
	v_lshrrev_b32_e32 v7, 21, v100
	v_cmp_eq_u32_e32 vcc, v7, v6
	s_and_saveexec_b64 s[0:1], vcc
	v_lshrrev_b32_e32 v7, 13, v100
	v_bfe_u32 v8, v100, 10, 11
	v_bitop3_b32 v7, v7, v8, 28 bitop3:0x6c
	v_lshl_add_u32 v7, v7, 2, v40
	ds_add_u32 v7, v186
	s_or_b64 exec, exec, s[0:1]
	v_lshrrev_b32_e32 v7, 21, v99
	v_cmp_eq_u32_e32 vcc, v7, v6
	s_and_saveexec_b64 s[0:1], vcc
	v_lshrrev_b32_e32 v7, 13, v99
	v_bfe_u32 v8, v99, 10, 11
	v_bitop3_b32 v7, v7, v8, 28 bitop3:0x6c
	v_lshl_add_u32 v7, v7, 2, v40
	ds_add_u32 v7, v186
	s_or_b64 exec, exec, s[0:1]
	v_lshrrev_b32_e32 v7, 21, v98
	v_cmp_eq_u32_e32 vcc, v7, v6
	s_and_saveexec_b64 s[0:1], vcc
	v_lshrrev_b32_e32 v7, 13, v98
	v_bfe_u32 v8, v98, 10, 11
	v_bitop3_b32 v7, v7, v8, 28 bitop3:0x6c
	v_lshl_add_u32 v7, v7, 2, v40
	ds_add_u32 v7, v186
	s_or_b64 exec, exec, s[0:1]
.Ll2s_10:
	s_cmpk_lt_i32 s77, 0x90
	s_cbranch_scc0 .LBB0_1640

.LBB0_1499:
	v_xor_b32_e32 v7, v12, v93
	v_xor_b32_e32 v8, v12, v92
	v_xor_b32_e32 v9, v12, v91
	v_xor_b32_e32 v10, v12, v90
	v_min3_u32 v7, v7, v8, v9
	v_min_u32_e32 v7, v7, v10
	v_cmp_gt_u32_e32 vcc, 0x200000, v7
	s_cbranch_vccz .Ll2s_11
	v_lshrrev_b32_e32 v7, 21, v93
	s_waitcnt lgkmcnt(0)
	v_cmp_eq_u32_e32 vcc, v7, v6
	s_and_saveexec_b64 s[0:1], vcc
	v_lshrrev_b32_e32 v7, 13, v93
	v_bfe_u32 v8, v93, 10, 11
	v_bitop3_b32 v7, v7, v8, 28 bitop3:0x6c
	v_lshl_add_u32 v7, v7, 2, v40
	ds_add_u32 v7, v186
	s_or_b64 exec, exec, s[0:1]
	v_lshrrev_b32_e32 v7, 21, v92
	v_cmp_eq_u32_e32 vcc, v7, v6
	s_and_saveexec_b64 s[0:1], vcc
	v_lshrrev_b32_e32 v7, 13, v92
	v_bfe_u32 v8, v92, 10, 11
	v_bitop3_b32 v7, v7, v8, 28 bitop3:0x6c
	v_lshl_add_u32 v7, v7, 2, v40
	ds_add_u32 v7, v186
	s_or_b64 exec, exec, s[0:1]
	v_lshrrev_b32_e32 v7, 21, v91
	v_cmp_eq_u32_e32 vcc, v7, v6
	s_and_saveexec_b64 s[0:1], vcc
	v_lshrrev_b32_e32 v7, 13, v91
	v_bfe_u32 v8, v91, 10, 11
	v_bitop3_b32 v7, v7, v8, 28 bitop3:0x6c
	v_lshl_add_u32 v7, v7, 2, v40
	ds_add_u32 v7, v186
	s_or_b64 exec, exec, s[0:1]
	v_lshrrev_b32_e32 v7, 21, v90
	v_cmp_eq_u32_e32 vcc, v7, v6
	s_and_saveexec_b64 s[0:1], vcc
	v_lshrrev_b32_e32 v7, 13, v90
	v_bfe_u32 v8, v90, 10, 11
	v_bitop3_b32 v7, v7, v8, 28 bitop3:0x6c
	v_lshl_add_u32 v7, v7, 2, v40
	ds_add_u32 v7, v186
	s_or_b64 exec, exec, s[0:1]
.Ll2s_11:
	s_cmpk_lt_i32 s77, 0xa0
	s_cbranch_scc0 .LBB0_1650

.LBB0_1509:
	v_xor_b32_e32 v7, v12, v85
	v_xor_b32_e32 v8, v12, v84
	v_xor_b32_e32 v9, v12, v83
	v_xor_b32_e32 v10, v12, v82
	v_min3_u32 v7, v7, v8, v9
	v_min_u32_e32 v7, v7, v10
	v_cmp_gt_u32_e32 vcc, 0x200000, v7
	s_cbranch_vccz .Ll2s_12
	v_lshrrev_b32_e32 v7, 21, v85
	s_waitcnt lgkmcnt(0)
	v_cmp_eq_u32_e32 vcc, v7, v6
	s_and_saveexec_b64 s[0:1], vcc
	v_lshrrev_b32_e32 v7, 13, v85
	v_bfe_u32 v8, v85, 10, 11
	v_bitop3_b32 v7, v7, v8, 28 bitop3:0x6c
	v_lshl_add_u32 v7, v7, 2, v40
	ds_add_u32 v7, v186
	s_or_b64 exec, exec, s[0:1]
	v_lshrrev_b32_e32 v7, 21, v84
	v_cmp_eq_u32_e32 vcc, v7, v6
	s_and_saveexec_b64 s[0:1], vcc
	v_lshrrev_b32_e32 v7, 13, v84
	v_bfe_u32 v8, v84, 10, 11
	v_bitop3_b32 v7, v7, v8, 28 bitop3:0x6c
	v_lshl_add_u32 v7, v7, 2, v40
	ds_add_u32 v7, v186
	s_or_b64 exec, exec, s[0:1]
	v_lshrrev_b32_e32 v7, 21, v83
	v_cmp_eq_u32_e32 vcc, v7, v6
	s_and_saveexec_b64 s[0:1], vcc
	v_lshrrev_b32_e32 v7, 13, v83
	v_bfe_u32 v8, v83, 10, 11
	v_bitop3_b32 v7, v7, v8, 28 bitop3:0x6c
	v_lshl_add_u32 v7, v7, 2, v40
	ds_add_u32 v7, v186
	s_or_b64 exec, exec, s[0:1]
	v_lshrrev_b32_e32 v7, 21, v82
	v_cmp_eq_u32_e32 vcc, v7, v6
	s_and_saveexec_b64 s[0:1], vcc
	v_lshrrev_b32_e32 v7, 13, v82
	v_bfe_u32 v8, v82, 10, 11
	v_bitop3_b32 v7, v7, v8, 28 bitop3:0x6c
	v_lshl_add_u32 v7, v7, 2, v40
	ds_add_u32 v7, v186
	s_or_b64 exec, exec, s[0:1]
.Ll2s_12:
	s_cmpk_lt_i32 s77, 0xb0
	s_cbranch_scc0 .LBB0_1660

.LBB0_1519:
	v_xor_b32_e32 v7, v12, v77
	v_xor_b32_e32 v8, v12, v76
	v_xor_b32_e32 v9, v12, v75
	v_xor_b32_e32 v10, v12, v74
	v_min3_u32 v7, v7, v8, v9
	v_min_u32_e32 v7, v7, v10
	v_cmp_gt_u32_e32 vcc, 0x200000, v7
	s_cbranch_vccz .Ll2s_13
	v_lshrrev_b32_e32 v7, 21, v77
	s_waitcnt lgkmcnt(0)
	v_cmp_eq_u32_e32 vcc, v7, v6
	s_and_saveexec_b64 s[0:1], vcc
	v_lshrrev_b32_e32 v7, 13, v77
	v_bfe_u32 v8, v77, 10, 11
	v_bitop3_b32 v7, v7, v8, 28 bitop3:0x6c
	v_lshl_add_u32 v7, v7, 2, v40
	ds_add_u32 v7, v186
	s_or_b64 exec, exec, s[0:1]
	v_lshrrev_b32_e32 v7, 21, v76
	v_cmp_eq_u32_e32 vcc, v7, v6
	s_and_saveexec_b64 s[0:1], vcc
	v_lshrrev_b32_e32 v7, 13, v76
	v_bfe_u32 v8, v76, 10, 11
	v_bitop3_b32 v7, v7, v8, 28 bitop3:0x6c
	v_lshl_add_u32 v7, v7, 2, v40
	ds_add_u32 v7, v186
	s_or_b64 exec, exec, s[0:1]
	v_lshrrev_b32_e32 v7, 21, v75
	v_cmp_eq_u32_e32 vcc, v7, v6
	s_and_saveexec_b64 s[0:1], vcc
	v_lshrrev_b32_e32 v7, 13, v75
	v_bfe_u32 v8, v75, 10, 11
	v_bitop3_b32 v7, v7, v8, 28 bitop3:0x6c
	v_lshl_add_u32 v7, v7, 2, v40
	ds_add_u32 v7, v186
	s_or_b64 exec, exec, s[0:1]
	v_lshrrev_b32_e32 v7, 21, v74
	v_cmp_eq_u32_e32 vcc, v7, v6
	s_and_saveexec_b64 s[0:1], vcc
	v_lshrrev_b32_e32 v7, 13, v74
	v_bfe_u32 v8, v74, 10, 11
	v_bitop3_b32 v7, v7, v8, 28 bitop3:0x6c
	v_lshl_add_u32 v7, v7, 2, v40
	ds_add_u32 v7, v186
	s_or_b64 exec, exec, s[0:1]
.Ll2s_13:
	s_cmpk_lt_i32 s77, 0xc0
	s_cbranch_scc0 .LBB0_1670

.LBB0_1529:
	v_xor_b32_e32 v7, v12, v69
	v_xor_b32_e32 v8, v12, v68
	v_xor_b32_e32 v9, v12, v67
	v_xor_b32_e32 v10, v12, v66
	v_min3_u32 v7, v7, v8, v9
	v_min_u32_e32 v7, v7, v10
	v_cmp_gt_u32_e32 vcc, 0x200000, v7
	s_cbranch_vccz .Ll2s_14
	v_lshrrev_b32_e32 v7, 21, v69
	s_waitcnt lgkmcnt(0)
	v_cmp_eq_u32_e32 vcc, v7, v6
	s_and_saveexec_b64 s[0:1], vcc
	v_lshrrev_b32_e32 v7, 13, v69
	v_bfe_u32 v8, v69, 10, 11
	v_bitop3_b32 v7, v7, v8, 28 bitop3:0x6c
	v_lshl_add_u32 v7, v7, 2, v40
	ds_add_u32 v7, v186
	s_or_b64 exec, exec, s[0:1]
	v_lshrrev_b32_e32 v7, 21, v68
	v_cmp_eq_u32_e32 vcc, v7, v6
	s_and_saveexec_b64 s[0:1], vcc
	v_lshrrev_b32_e32 v7, 13, v68
	v_bfe_u32 v8, v68, 10, 11
	v_bitop3_b32 v7, v7, v8, 28 bitop3:0x6c
	v_lshl_add_u32 v7, v7, 2, v40
	ds_add_u32 v7, v186
	s_or_b64 exec, exec, s[0:1]
	v_lshrrev_b32_e32 v7, 21, v67
	v_cmp_eq_u32_e32 vcc, v7, v6
	s_and_saveexec_b64 s[0:1], vcc
	v_lshrrev_b32_e32 v7, 13, v67
	v_bfe_u32 v8, v67, 10, 11
	v_bitop3_b32 v7, v7, v8, 28 bitop3:0x6c
	v_lshl_add_u32 v7, v7, 2, v40
	ds_add_u32 v7, v186
	s_or_b64 exec, exec, s[0:1]
	v_lshrrev_b32_e32 v7, 21, v66
	v_cmp_eq_u32_e32 vcc, v7, v6
	s_and_saveexec_b64 s[0:1], vcc
	v_lshrrev_b32_e32 v7, 13, v66
	v_bfe_u32 v8, v66, 10, 11
	v_bitop3_b32 v7, v7, v8, 28 bitop3:0x6c
	v_lshl_add_u32 v7, v7, 2, v40
	ds_add_u32 v7, v186
	s_or_b64 exec, exec, s[0:1]
.Ll2s_14:
	s_cmpk_lt_i32 s77, 0xd0
	s_cbranch_scc0 .LBB0_1680

.LBB0_1539:
	v_xor_b32_e32 v7, v12, v61
	v_xor_b32_e32 v8, v12, v60
	v_xor_b32_e32 v9, v12, v59
	v_xor_b32_e32 v10, v12, v58
	v_min3_u32 v7, v7, v8, v9
	v_min_u32_e32 v7, v7, v10
	v_cmp_gt_u32_e32 vcc, 0x200000, v7
	s_cbranch_vccz .Ll2s_15
	v_lshrrev_b32_e32 v7, 21, v61
	s_waitcnt lgkmcnt(0)
	v_cmp_eq_u32_e32 vcc, v7, v6
	s_and_saveexec_b64 s[0:1], vcc
	v_lshrrev_b32_e32 v7, 13, v61
	v_bfe_u32 v8, v61, 10, 11
	v_bitop3_b32 v7, v7, v8, 28 bitop3:0x6c
	v_lshl_add_u32 v7, v7, 2, v40
	ds_add_u32 v7, v186
	s_or_b64 exec, exec, s[0:1]
	v_lshrrev_b32_e32 v7, 21, v60
	v_cmp_eq_u32_e32 vcc, v7, v6
	s_and_saveexec_b64 s[0:1], vcc
	v_lshrrev_b32_e32 v7, 13, v60
	v_bfe_u32 v8, v60, 10, 11
	v_bitop3_b32 v7, v7, v8, 28 bitop3:0x6c
	v_lshl_add_u32 v7, v7, 2, v40
	ds_add_u32 v7, v186
	s_or_b64 exec, exec, s[0:1]
	v_lshrrev_b32_e32 v7, 21, v59
	v_cmp_eq_u32_e32 vcc, v7, v6
	s_and_saveexec_b64 s[0:1], vcc
	v_lshrrev_b32_e32 v7, 13, v59
	v_bfe_u32 v8, v59, 10, 11
	v_bitop3_b32 v7, v7, v8, 28 bitop3:0x6c
	v_lshl_add_u32 v7, v7, 2, v40
	ds_add_u32 v7, v186
	s_or_b64 exec, exec, s[0:1]
	v_lshrrev_b32_e32 v7, 21, v58
	v_cmp_eq_u32_e32 vcc, v7, v6
	s_and_saveexec_b64 s[0:1], vcc
	v_lshrrev_b32_e32 v7, 13, v58
	v_bfe_u32 v8, v58, 10, 11
	v_bitop3_b32 v7, v7, v8, 28 bitop3:0x6c
	v_lshl_add_u32 v7, v7, 2, v40
	ds_add_u32 v7, v186
	s_or_b64 exec, exec, s[0:1]
.Ll2s_15:
	s_cmpk_lt_i32 s77, 0xe0
	s_cbranch_scc0 .LBB0_1690

.LBB0_1549:
	v_xor_b32_e32 v7, v12, v53
	v_xor_b32_e32 v8, v12, v52
	v_xor_b32_e32 v9, v12, v51
	v_xor_b32_e32 v10, v12, v50
	v_min3_u32 v7, v7, v8, v9
	v_min_u32_e32 v7, v7, v10
	v_cmp_gt_u32_e32 vcc, 0x200000, v7
	s_cbranch_vccz .Ll2s_16
	v_lshrrev_b32_e32 v7, 21, v53
	s_waitcnt lgkmcnt(0)
	v_cmp_eq_u32_e32 vcc, v7, v6
	s_and_saveexec_b64 s[0:1], vcc
	v_lshrrev_b32_e32 v7, 13, v53
	v_bfe_u32 v8, v53, 10, 11
	v_bitop3_b32 v7, v7, v8, 28 bitop3:0x6c
	v_lshl_add_u32 v7, v7, 2, v40
	ds_add_u32 v7, v186
	s_or_b64 exec, exec, s[0:1]
	v_lshrrev_b32_e32 v7, 21, v52
	v_cmp_eq_u32_e32 vcc, v7, v6
	s_and_saveexec_b64 s[0:1], vcc
	v_lshrrev_b32_e32 v7, 13, v52
	v_bfe_u32 v8, v52, 10, 11
	v_bitop3_b32 v7, v7, v8, 28 bitop3:0x6c
	v_lshl_add_u32 v7, v7, 2, v40
	ds_add_u32 v7, v186
	s_or_b64 exec, exec, s[0:1]
	v_lshrrev_b32_e32 v7, 21, v51
	v_cmp_eq_u32_e32 vcc, v7, v6
	s_and_saveexec_b64 s[0:1], vcc
	v_lshrrev_b32_e32 v7, 13, v51
	v_bfe_u32 v8, v51, 10, 11
	v_bitop3_b32 v7, v7, v8, 28 bitop3:0x6c
	v_lshl_add_u32 v7, v7, 2, v40
	ds_add_u32 v7, v186
	s_or_b64 exec, exec, s[0:1]
	v_lshrrev_b32_e32 v7, 21, v50
	v_cmp_eq_u32_e32 vcc, v7, v6
	s_and_saveexec_b64 s[0:1], vcc
	v_lshrrev_b32_e32 v7, 13, v50
	v_bfe_u32 v8, v50, 10, 11
	v_bitop3_b32 v7, v7, v8, 28 bitop3:0x6c
	v_lshl_add_u32 v7, v7, 2, v40
	ds_add_u32 v7, v186
	s_or_b64 exec, exec, s[0:1]
.Ll2s_16:
	s_cmpk_lt_i32 s77, 0xf0
	s_cbranch_scc0 .LBB0_1700

.LBB0_1560:
	v_xor_b32_e32 v7, v12, v162
	v_xor_b32_e32 v8, v12, v161
	v_xor_b32_e32 v9, v12, v160
	v_xor_b32_e32 v10, v12, v159
	v_min3_u32 v7, v7, v8, v9
	v_min_u32_e32 v7, v7, v10
	v_cmp_gt_u32_e32 vcc, 0x200000, v7
	s_cbranch_vccz .Ll2s_17
	v_lshrrev_b32_e32 v7, 21, v162
	s_waitcnt lgkmcnt(0)
	v_cmp_eq_u32_e32 vcc, v7, v6
	s_and_saveexec_b64 s[0:1], vcc
	v_lshrrev_b32_e32 v7, 13, v162
	v_bfe_u32 v8, v162, 10, 11
	v_bitop3_b32 v7, v7, v8, 28 bitop3:0x6c
	v_lshl_add_u32 v7, v7, 2, v40
	ds_add_u32 v7, v186
	s_or_b64 exec, exec, s[0:1]
	v_lshrrev_b32_e32 v7, 21, v161
	v_cmp_eq_u32_e32 vcc, v7, v6
	s_and_saveexec_b64 s[0:1], vcc
	v_lshrrev_b32_e32 v7, 13, v161
	v_bfe_u32 v8, v161, 10, 11
	v_bitop3_b32 v7, v7, v8, 28 bitop3:0x6c
	v_lshl_add_u32 v7, v7, 2, v40
	ds_add_u32 v7, v186
	s_or_b64 exec, exec, s[0:1]
	v_lshrrev_b32_e32 v7, 21, v160
	v_cmp_eq_u32_e32 vcc, v7, v6
	s_and_saveexec_b64 s[0:1], vcc
	v_lshrrev_b32_e32 v7, 13, v160
	v_bfe_u32 v8, v160, 10, 11
	v_bitop3_b32 v7, v7, v8, 28 bitop3:0x6c
	v_lshl_add_u32 v7, v7, 2, v40
	ds_add_u32 v7, v186
	s_or_b64 exec, exec, s[0:1]
	v_lshrrev_b32_e32 v7, 21, v159
	v_cmp_eq_u32_e32 vcc, v7, v6
	s_and_saveexec_b64 s[0:1], vcc
	v_lshrrev_b32_e32 v7, 13, v159
	v_bfe_u32 v8, v159, 10, 11
	v_bitop3_b32 v7, v7, v8, 28 bitop3:0x6c
	v_lshl_add_u32 v7, v7, 2, v40
	ds_add_u32 v7, v186
	s_or_b64 exec, exec, s[0:1]
.Ll2s_17:
	s_cmp_lt_i32 s77, 24
	s_cbranch_scc0 .LBB0_1419

.LBB0_1570:
	v_xor_b32_e32 v7, v12, v154
	v_xor_b32_e32 v8, v12, v153
	v_xor_b32_e32 v9, v12, v152
	v_xor_b32_e32 v10, v12, v151
	v_min3_u32 v7, v7, v8, v9
	v_min_u32_e32 v7, v7, v10
	v_cmp_gt_u32_e32 vcc, 0x200000, v7
	s_cbranch_vccz .Ll2s_18
	v_lshrrev_b32_e32 v7, 21, v154
	s_waitcnt lgkmcnt(0)
	v_cmp_eq_u32_e32 vcc, v7, v6
	s_and_saveexec_b64 s[0:1], vcc
	v_lshrrev_b32_e32 v7, 13, v154
	v_bfe_u32 v8, v154, 10, 11
	v_bitop3_b32 v7, v7, v8, 28 bitop3:0x6c
	v_lshl_add_u32 v7, v7, 2, v40
	ds_add_u32 v7, v186
	s_or_b64 exec, exec, s[0:1]
	v_lshrrev_b32_e32 v7, 21, v153
	v_cmp_eq_u32_e32 vcc, v7, v6
	s_and_saveexec_b64 s[0:1], vcc
	v_lshrrev_b32_e32 v7, 13, v153
	v_bfe_u32 v8, v153, 10, 11
	v_bitop3_b32 v7, v7, v8, 28 bitop3:0x6c
	v_lshl_add_u32 v7, v7, 2, v40
	ds_add_u32 v7, v186
	s_or_b64 exec, exec, s[0:1]
	v_lshrrev_b32_e32 v7, 21, v152
	v_cmp_eq_u32_e32 vcc, v7, v6
	s_and_saveexec_b64 s[0:1], vcc
	v_lshrrev_b32_e32 v7, 13, v152
	v_bfe_u32 v8, v152, 10, 11
	v_bitop3_b32 v7, v7, v8, 28 bitop3:0x6c
	v_lshl_add_u32 v7, v7, 2, v40
	ds_add_u32 v7, v186
	s_or_b64 exec, exec, s[0:1]
	v_lshrrev_b32_e32 v7, 21, v151
	v_cmp_eq_u32_e32 vcc, v7, v6
	s_and_saveexec_b64 s[0:1], vcc
	v_lshrrev_b32_e32 v7, 13, v151
	v_bfe_u32 v8, v151, 10, 11
	v_bitop3_b32 v7, v7, v8, 28 bitop3:0x6c
	v_lshl_add_u32 v7, v7, 2, v40
	ds_add_u32 v7, v186
	s_or_b64 exec, exec, s[0:1]
.Ll2s_18:
	s_cmp_lt_i32 s77, 40
	s_cbranch_scc0 .LBB0_1429

.LBB0_1580:
	v_xor_b32_e32 v7, v12, v146
	v_xor_b32_e32 v8, v12, v145
	v_xor_b32_e32 v9, v12, v144
	v_xor_b32_e32 v10, v12, v143
	v_min3_u32 v7, v7, v8, v9
	v_min_u32_e32 v7, v7, v10
	v_cmp_gt_u32_e32 vcc, 0x200000, v7
	s_cbranch_vccz .Ll2s_19
	v_lshrrev_b32_e32 v7, 21, v146
	s_waitcnt lgkmcnt(0)
	v_cmp_eq_u32_e32 vcc, v7, v6
	s_and_saveexec_b64 s[0:1], vcc
	v_lshrrev_b32_e32 v7, 13, v146
	v_bfe_u32 v8, v146, 10, 11
	v_bitop3_b32 v7, v7, v8, 28 bitop3:0x6c
	v_lshl_add_u32 v7, v7, 2, v40
	ds_add_u32 v7, v186
	s_or_b64 exec, exec, s[0:1]
	v_lshrrev_b32_e32 v7, 21, v145
	v_cmp_eq_u32_e32 vcc, v7, v6
	s_and_saveexec_b64 s[0:1], vcc
	v_lshrrev_b32_e32 v7, 13, v145
	v_bfe_u32 v8, v145, 10, 11
	v_bitop3_b32 v7, v7, v8, 28 bitop3:0x6c
	v_lshl_add_u32 v7, v7, 2, v40
	ds_add_u32 v7, v186
	s_or_b64 exec, exec, s[0:1]
	v_lshrrev_b32_e32 v7, 21, v144
	v_cmp_eq_u32_e32 vcc, v7, v6
	s_and_saveexec_b64 s[0:1], vcc
	v_lshrrev_b32_e32 v7, 13, v144
	v_bfe_u32 v8, v144, 10, 11
	v_bitop3_b32 v7, v7, v8, 28 bitop3:0x6c
	v_lshl_add_u32 v7, v7, 2, v40
	ds_add_u32 v7, v186
	s_or_b64 exec, exec, s[0:1]
	v_lshrrev_b32_e32 v7, 21, v143
	v_cmp_eq_u32_e32 vcc, v7, v6
	s_and_saveexec_b64 s[0:1], vcc
	v_lshrrev_b32_e32 v7, 13, v143
	v_bfe_u32 v8, v143, 10, 11
	v_bitop3_b32 v7, v7, v8, 28 bitop3:0x6c
	v_lshl_add_u32 v7, v7, 2, v40
	ds_add_u32 v7, v186
	s_or_b64 exec, exec, s[0:1]
.Ll2s_19:
	s_cmp_lt_i32 s77, 56
	s_cbranch_scc0 .LBB0_1439

.LBB0_1590:
	v_xor_b32_e32 v7, v12, v138
	v_xor_b32_e32 v8, v12, v137
	v_xor_b32_e32 v9, v12, v136
	v_xor_b32_e32 v10, v12, v135
	v_min3_u32 v7, v7, v8, v9
	v_min_u32_e32 v7, v7, v10
	v_cmp_gt_u32_e32 vcc, 0x200000, v7
	s_cbranch_vccz .Ll2s_20
	v_lshrrev_b32_e32 v7, 21, v138
	s_waitcnt lgkmcnt(0)
	v_cmp_eq_u32_e32 vcc, v7, v6
	s_and_saveexec_b64 s[0:1], vcc
	v_lshrrev_b32_e32 v7, 13, v138
	v_bfe_u32 v8, v138, 10, 11
	v_bitop3_b32 v7, v7, v8, 28 bitop3:0x6c
	v_lshl_add_u32 v7, v7, 2, v40
	ds_add_u32 v7, v186
	s_or_b64 exec, exec, s[0:1]
	v_lshrrev_b32_e32 v7, 21, v137
	v_cmp_eq_u32_e32 vcc, v7, v6
	s_and_saveexec_b64 s[0:1], vcc
	v_lshrrev_b32_e32 v7, 13, v137
	v_bfe_u32 v8, v137, 10, 11
	v_bitop3_b32 v7, v7, v8, 28 bitop3:0x6c
	v_lshl_add_u32 v7, v7, 2, v40
	ds_add_u32 v7, v186
	s_or_b64 exec, exec, s[0:1]
	v_lshrrev_b32_e32 v7, 21, v136
	v_cmp_eq_u32_e32 vcc, v7, v6
	s_and_saveexec_b64 s[0:1], vcc
	v_lshrrev_b32_e32 v7, 13, v136
	v_bfe_u32 v8, v136, 10, 11
	v_bitop3_b32 v7, v7, v8, 28 bitop3:0x6c
	v_lshl_add_u32 v7, v7, 2, v40
	ds_add_u32 v7, v186
	s_or_b64 exec, exec, s[0:1]
	v_lshrrev_b32_e32 v7, 21, v135
	v_cmp_eq_u32_e32 vcc, v7, v6
	s_and_saveexec_b64 s[0:1], vcc
	v_lshrrev_b32_e32 v7, 13, v135
	v_bfe_u32 v8, v135, 10, 11
	v_bitop3_b32 v7, v7, v8, 28 bitop3:0x6c
	v_lshl_add_u32 v7, v7, 2, v40
	ds_add_u32 v7, v186
	s_or_b64 exec, exec, s[0:1]
.Ll2s_20:
	s_cmpk_lt_i32 s77, 0x48
	s_cbranch_scc0 .LBB0_1449

.LBB0_1600:
	v_xor_b32_e32 v7, v12, v130
	v_xor_b32_e32 v8, v12, v129
	v_xor_b32_e32 v9, v12, v128
	v_xor_b32_e32 v10, v12, v127
	v_min3_u32 v7, v7, v8, v9
	v_min_u32_e32 v7, v7, v10
	v_cmp_gt_u32_e32 vcc, 0x200000, v7
	s_cbranch_vccz .Ll2s_21
	v_lshrrev_b32_e32 v7, 21, v130
	s_waitcnt lgkmcnt(0)
	v_cmp_eq_u32_e32 vcc, v7, v6
	s_and_saveexec_b64 s[0:1], vcc
	v_lshrrev_b32_e32 v7, 13, v130
	v_bfe_u32 v8, v130, 10, 11
	v_bitop3_b32 v7, v7, v8, 28 bitop3:0x6c
	v_lshl_add_u32 v7, v7, 2, v40
	ds_add_u32 v7, v186
	s_or_b64 exec, exec, s[0:1]
	v_lshrrev_b32_e32 v7, 21, v129
	v_cmp_eq_u32_e32 vcc, v7, v6
	s_and_saveexec_b64 s[0:1], vcc
	v_lshrrev_b32_e32 v7, 13, v129
	v_bfe_u32 v8, v129, 10, 11
	v_bitop3_b32 v7, v7, v8, 28 bitop3:0x6c
	v_lshl_add_u32 v7, v7, 2, v40
	ds_add_u32 v7, v186
	s_or_b64 exec, exec, s[0:1]
	v_lshrrev_b32_e32 v7, 21, v128
	v_cmp_eq_u32_e32 vcc, v7, v6
	s_and_saveexec_b64 s[0:1], vcc
	v_lshrrev_b32_e32 v7, 13, v128
	v_bfe_u32 v8, v128, 10, 11
	v_bitop3_b32 v7, v7, v8, 28 bitop3:0x6c
	v_lshl_add_u32 v7, v7, 2, v40
	ds_add_u32 v7, v186
	s_or_b64 exec, exec, s[0:1]
	v_lshrrev_b32_e32 v7, 21, v127
	v_cmp_eq_u32_e32 vcc, v7, v6
	s_and_saveexec_b64 s[0:1], vcc
	v_lshrrev_b32_e32 v7, 13, v127
	v_bfe_u32 v8, v127, 10, 11
	v_bitop3_b32 v7, v7, v8, 28 bitop3:0x6c
	v_lshl_add_u32 v7, v7, 2, v40
	ds_add_u32 v7, v186
	s_or_b64 exec, exec, s[0:1]
.Ll2s_21:
	s_cmpk_lt_i32 s77, 0x58
	s_cbranch_scc0 .LBB0_1459

.LBB0_1610:
	v_xor_b32_e32 v7, v12, v122
	v_xor_b32_e32 v8, v12, v121
	v_xor_b32_e32 v9, v12, v120
	v_xor_b32_e32 v10, v12, v119
	v_min3_u32 v7, v7, v8, v9
	v_min_u32_e32 v7, v7, v10
	v_cmp_gt_u32_e32 vcc, 0x200000, v7
	s_cbranch_vccz .Ll2s_22
	v_lshrrev_b32_e32 v7, 21, v122
	s_waitcnt lgkmcnt(0)
	v_cmp_eq_u32_e32 vcc, v7, v6
	s_and_saveexec_b64 s[0:1], vcc
	v_lshrrev_b32_e32 v7, 13, v122
	v_bfe_u32 v8, v122, 10, 11
	v_bitop3_b32 v7, v7, v8, 28 bitop3:0x6c
	v_lshl_add_u32 v7, v7, 2, v40
	ds_add_u32 v7, v186
	s_or_b64 exec, exec, s[0:1]
	v_lshrrev_b32_e32 v7, 21, v121
	v_cmp_eq_u32_e32 vcc, v7, v6
	s_and_saveexec_b64 s[0:1], vcc
	v_lshrrev_b32_e32 v7, 13, v121
	v_bfe_u32 v8, v121, 10, 11
	v_bitop3_b32 v7, v7, v8, 28 bitop3:0x6c
	v_lshl_add_u32 v7, v7, 2, v40
	ds_add_u32 v7, v186
	s_or_b64 exec, exec, s[0:1]
	v_lshrrev_b32_e32 v7, 21, v120
	v_cmp_eq_u32_e32 vcc, v7, v6
	s_and_saveexec_b64 s[0:1], vcc
	v_lshrrev_b32_e32 v7, 13, v120
	v_bfe_u32 v8, v120, 10, 11
	v_bitop3_b32 v7, v7, v8, 28 bitop3:0x6c
	v_lshl_add_u32 v7, v7, 2, v40
	ds_add_u32 v7, v186
	s_or_b64 exec, exec, s[0:1]
	v_lshrrev_b32_e32 v7, 21, v119
	v_cmp_eq_u32_e32 vcc, v7, v6
	s_and_saveexec_b64 s[0:1], vcc
	v_lshrrev_b32_e32 v7, 13, v119
	v_bfe_u32 v8, v119, 10, 11
	v_bitop3_b32 v7, v7, v8, 28 bitop3:0x6c
	v_lshl_add_u32 v7, v7, 2, v40
	ds_add_u32 v7, v186
	s_or_b64 exec, exec, s[0:1]
.Ll2s_22:
	s_cmpk_lt_i32 s77, 0x68
	s_cbranch_scc0 .LBB0_1469

.LBB0_1620:
	v_xor_b32_e32 v7, v12, v113
	v_xor_b32_e32 v8, v12, v112
	v_xor_b32_e32 v9, v12, v111
	v_xor_b32_e32 v10, v12, v110
	v_min3_u32 v7, v7, v8, v9
	v_min_u32_e32 v7, v7, v10
	v_cmp_gt_u32_e32 vcc, 0x200000, v7
	s_cbranch_vccz .Ll2s_23
	v_lshrrev_b32_e32 v7, 21, v113
	s_waitcnt lgkmcnt(0)
	v_cmp_eq_u32_e32 vcc, v7, v6
	s_and_saveexec_b64 s[0:1], vcc
	v_lshrrev_b32_e32 v7, 13, v113
	v_bfe_u32 v8, v113, 10, 11
	v_bitop3_b32 v7, v7, v8, 28 bitop3:0x6c
	v_lshl_add_u32 v7, v7, 2, v40
	ds_add_u32 v7, v186
	s_or_b64 exec, exec, s[0:1]
	v_lshrrev_b32_e32 v7, 21, v112
	v_cmp_eq_u32_e32 vcc, v7, v6
	s_and_saveexec_b64 s[0:1], vcc
	v_lshrrev_b32_e32 v7, 13, v112
	v_bfe_u32 v8, v112, 10, 11
	v_bitop3_b32 v7, v7, v8, 28 bitop3:0x6c
	v_lshl_add_u32 v7, v7, 2, v40
	ds_add_u32 v7, v186
	s_or_b64 exec, exec, s[0:1]
	v_lshrrev_b32_e32 v7, 21, v111
	v_cmp_eq_u32_e32 vcc, v7, v6
	s_and_saveexec_b64 s[0:1], vcc
	v_lshrrev_b32_e32 v7, 13, v111
	v_bfe_u32 v8, v111, 10, 11
	v_bitop3_b32 v7, v7, v8, 28 bitop3:0x6c
	v_lshl_add_u32 v7, v7, 2, v40
	ds_add_u32 v7, v186
	s_or_b64 exec, exec, s[0:1]
	v_lshrrev_b32_e32 v7, 21, v110
	v_cmp_eq_u32_e32 vcc, v7, v6
	s_and_saveexec_b64 s[0:1], vcc
	v_lshrrev_b32_e32 v7, 13, v110
	v_bfe_u32 v8, v110, 10, 11
	v_bitop3_b32 v7, v7, v8, 28 bitop3:0x6c
	v_lshl_add_u32 v7, v7, 2, v40
	ds_add_u32 v7, v186
	s_or_b64 exec, exec, s[0:1]
.Ll2s_23:
	s_cmpk_lt_i32 s77, 0x78
	s_cbranch_scc0 .LBB0_1479

.LBB0_1630:
	v_xor_b32_e32 v7, v12, v106
	v_xor_b32_e32 v8, v12, v104
	v_xor_b32_e32 v9, v12, v103
	v_xor_b32_e32 v10, v12, v102
	v_min3_u32 v7, v7, v8, v9
	v_min_u32_e32 v7, v7, v10
	v_cmp_gt_u32_e32 vcc, 0x200000, v7
	s_cbranch_vccz .Ll2s_24
	v_lshrrev_b32_e32 v7, 21, v106
	s_waitcnt lgkmcnt(0)
	v_cmp_eq_u32_e32 vcc, v7, v6
	s_and_saveexec_b64 s[0:1], vcc
	v_lshrrev_b32_e32 v7, 13, v106
	v_bfe_u32 v8, v106, 10, 11
	v_bitop3_b32 v7, v7, v8, 28 bitop3:0x6c
	v_lshl_add_u32 v7, v7, 2, v40
	ds_add_u32 v7, v186
	s_or_b64 exec, exec, s[0:1]
	v_lshrrev_b32_e32 v7, 21, v104
	v_cmp_eq_u32_e32 vcc, v7, v6
	s_and_saveexec_b64 s[0:1], vcc
	v_lshrrev_b32_e32 v7, 13, v104
	v_bfe_u32 v8, v104, 10, 11
	v_bitop3_b32 v7, v7, v8, 28 bitop3:0x6c
	v_lshl_add_u32 v7, v7, 2, v40
	ds_add_u32 v7, v186
	s_or_b64 exec, exec, s[0:1]
	v_lshrrev_b32_e32 v7, 21, v103
	v_cmp_eq_u32_e32 vcc, v7, v6
	s_and_saveexec_b64 s[0:1], vcc
	v_lshrrev_b32_e32 v7, 13, v103
	v_bfe_u32 v8, v103, 10, 11
	v_bitop3_b32 v7, v7, v8, 28 bitop3:0x6c
	v_lshl_add_u32 v7, v7, 2, v40
	ds_add_u32 v7, v186
	s_or_b64 exec, exec, s[0:1]
	v_lshrrev_b32_e32 v7, 21, v102
	v_cmp_eq_u32_e32 vcc, v7, v6
	s_and_saveexec_b64 s[0:1], vcc
	v_lshrrev_b32_e32 v7, 13, v102
	v_bfe_u32 v8, v102, 10, 11
	v_bitop3_b32 v7, v7, v8, 28 bitop3:0x6c
	v_lshl_add_u32 v7, v7, 2, v40
	ds_add_u32 v7, v186
	s_or_b64 exec, exec, s[0:1]
.Ll2s_24:
	s_cmpk_lt_i32 s77, 0x88
	s_cbranch_scc0 .LBB0_1489

.LBB0_1640:
	v_xor_b32_e32 v7, v12, v97
	v_xor_b32_e32 v8, v12, v96
	v_xor_b32_e32 v9, v12, v95
	v_xor_b32_e32 v10, v12, v94
	v_min3_u32 v7, v7, v8, v9
	v_min_u32_e32 v7, v7, v10
	v_cmp_gt_u32_e32 vcc, 0x200000, v7
	s_cbranch_vccz .Ll2s_25
	v_lshrrev_b32_e32 v7, 21, v97
	s_waitcnt lgkmcnt(0)
	v_cmp_eq_u32_e32 vcc, v7, v6
	s_and_saveexec_b64 s[0:1], vcc
	v_lshrrev_b32_e32 v7, 13, v97
	v_bfe_u32 v8, v97, 10, 11
	v_bitop3_b32 v7, v7, v8, 28 bitop3:0x6c
	v_lshl_add_u32 v7, v7, 2, v40
	ds_add_u32 v7, v186
	s_or_b64 exec, exec, s[0:1]
	v_lshrrev_b32_e32 v7, 21, v96
	v_cmp_eq_u32_e32 vcc, v7, v6
	s_and_saveexec_b64 s[0:1], vcc
	v_lshrrev_b32_e32 v7, 13, v96
	v_bfe_u32 v8, v96, 10, 11
	v_bitop3_b32 v7, v7, v8, 28 bitop3:0x6c
	v_lshl_add_u32 v7, v7, 2, v40
	ds_add_u32 v7, v186
	s_or_b64 exec, exec, s[0:1]
	v_lshrrev_b32_e32 v7, 21, v95
	v_cmp_eq_u32_e32 vcc, v7, v6
	s_and_saveexec_b64 s[0:1], vcc
	v_lshrrev_b32_e32 v7, 13, v95
	v_bfe_u32 v8, v95, 10, 11
	v_bitop3_b32 v7, v7, v8, 28 bitop3:0x6c
	v_lshl_add_u32 v7, v7, 2, v40
	ds_add_u32 v7, v186
	s_or_b64 exec, exec, s[0:1]
	v_lshrrev_b32_e32 v7, 21, v94
	v_cmp_eq_u32_e32 vcc, v7, v6
	s_and_saveexec_b64 s[0:1], vcc
	v_lshrrev_b32_e32 v7, 13, v94
	v_bfe_u32 v8, v94, 10, 11
	v_bitop3_b32 v7, v7, v8, 28 bitop3:0x6c
	v_lshl_add_u32 v7, v7, 2, v40
	ds_add_u32 v7, v186
	s_or_b64 exec, exec, s[0:1]
.Ll2s_25:
	s_cmpk_lt_i32 s77, 0x98
	s_cbranch_scc0 .LBB0_1499

.LBB0_1650:
	v_xor_b32_e32 v7, v12, v89
	v_xor_b32_e32 v8, v12, v88
	v_xor_b32_e32 v9, v12, v87
	v_xor_b32_e32 v10, v12, v86
	v_min3_u32 v7, v7, v8, v9
	v_min_u32_e32 v7, v7, v10
	v_cmp_gt_u32_e32 vcc, 0x200000, v7
	s_cbranch_vccz .Ll2s_26
	v_lshrrev_b32_e32 v7, 21, v89
	s_waitcnt lgkmcnt(0)
	v_cmp_eq_u32_e32 vcc, v7, v6
	s_and_saveexec_b64 s[0:1], vcc
	v_lshrrev_b32_e32 v7, 13, v89
	v_bfe_u32 v8, v89, 10, 11
	v_bitop3_b32 v7, v7, v8, 28 bitop3:0x6c
	v_lshl_add_u32 v7, v7, 2, v40
	ds_add_u32 v7, v186
	s_or_b64 exec, exec, s[0:1]
	v_lshrrev_b32_e32 v7, 21, v88
	v_cmp_eq_u32_e32 vcc, v7, v6
	s_and_saveexec_b64 s[0:1], vcc
	v_lshrrev_b32_e32 v7, 13, v88
	v_bfe_u32 v8, v88, 10, 11
	v_bitop3_b32 v7, v7, v8, 28 bitop3:0x6c
	v_lshl_add_u32 v7, v7, 2, v40
	ds_add_u32 v7, v186
	s_or_b64 exec, exec, s[0:1]
	v_lshrrev_b32_e32 v7, 21, v87
	v_cmp_eq_u32_e32 vcc, v7, v6
	s_and_saveexec_b64 s[0:1], vcc
	v_lshrrev_b32_e32 v7, 13, v87
	v_bfe_u32 v8, v87, 10, 11
	v_bitop3_b32 v7, v7, v8, 28 bitop3:0x6c
	v_lshl_add_u32 v7, v7, 2, v40
	ds_add_u32 v7, v186
	s_or_b64 exec, exec, s[0:1]
	v_lshrrev_b32_e32 v7, 21, v86
	v_cmp_eq_u32_e32 vcc, v7, v6
	s_and_saveexec_b64 s[0:1], vcc
	v_lshrrev_b32_e32 v7, 13, v86
	v_bfe_u32 v8, v86, 10, 11
	v_bitop3_b32 v7, v7, v8, 28 bitop3:0x6c
	v_lshl_add_u32 v7, v7, 2, v40
	ds_add_u32 v7, v186
	s_or_b64 exec, exec, s[0:1]
.Ll2s_26:
	s_cmpk_lt_i32 s77, 0xa8
	s_cbranch_scc0 .LBB0_1509

.LBB0_1660:
	v_xor_b32_e32 v7, v12, v81
	v_xor_b32_e32 v8, v12, v80
	v_xor_b32_e32 v9, v12, v79
	v_xor_b32_e32 v10, v12, v78
	v_min3_u32 v7, v7, v8, v9
	v_min_u32_e32 v7, v7, v10
	v_cmp_gt_u32_e32 vcc, 0x200000, v7
	s_cbranch_vccz .Ll2s_27
	v_lshrrev_b32_e32 v7, 21, v81
	s_waitcnt lgkmcnt(0)
	v_cmp_eq_u32_e32 vcc, v7, v6
	s_and_saveexec_b64 s[0:1], vcc
	v_lshrrev_b32_e32 v7, 13, v81
	v_bfe_u32 v8, v81, 10, 11
	v_bitop3_b32 v7, v7, v8, 28 bitop3:0x6c
	v_lshl_add_u32 v7, v7, 2, v40
	ds_add_u32 v7, v186
	s_or_b64 exec, exec, s[0:1]
	v_lshrrev_b32_e32 v7, 21, v80
	v_cmp_eq_u32_e32 vcc, v7, v6
	s_and_saveexec_b64 s[0:1], vcc
	v_lshrrev_b32_e32 v7, 13, v80
	v_bfe_u32 v8, v80, 10, 11
	v_bitop3_b32 v7, v7, v8, 28 bitop3:0x6c
	v_lshl_add_u32 v7, v7, 2, v40
	ds_add_u32 v7, v186
	s_or_b64 exec, exec, s[0:1]
	v_lshrrev_b32_e32 v7, 21, v79
	v_cmp_eq_u32_e32 vcc, v7, v6
	s_and_saveexec_b64 s[0:1], vcc
	v_lshrrev_b32_e32 v7, 13, v79
	v_bfe_u32 v8, v79, 10, 11
	v_bitop3_b32 v7, v7, v8, 28 bitop3:0x6c
	v_lshl_add_u32 v7, v7, 2, v40
	ds_add_u32 v7, v186
	s_or_b64 exec, exec, s[0:1]
	v_lshrrev_b32_e32 v7, 21, v78
	v_cmp_eq_u32_e32 vcc, v7, v6
	s_and_saveexec_b64 s[0:1], vcc
	v_lshrrev_b32_e32 v7, 13, v78
	v_bfe_u32 v8, v78, 10, 11
	v_bitop3_b32 v7, v7, v8, 28 bitop3:0x6c
	v_lshl_add_u32 v7, v7, 2, v40
	ds_add_u32 v7, v186
	s_or_b64 exec, exec, s[0:1]
.Ll2s_27:
	s_cmpk_lt_i32 s77, 0xb8
	s_cbranch_scc0 .LBB0_1519

.LBB0_1670:
	v_xor_b32_e32 v7, v12, v73
	v_xor_b32_e32 v8, v12, v72
	v_xor_b32_e32 v9, v12, v71
	v_xor_b32_e32 v10, v12, v70
	v_min3_u32 v7, v7, v8, v9
	v_min_u32_e32 v7, v7, v10
	v_cmp_gt_u32_e32 vcc, 0x200000, v7
	s_cbranch_vccz .Ll2s_28
	v_lshrrev_b32_e32 v7, 21, v73
	s_waitcnt lgkmcnt(0)
	v_cmp_eq_u32_e32 vcc, v7, v6
	s_and_saveexec_b64 s[0:1], vcc
	v_lshrrev_b32_e32 v7, 13, v73
	v_bfe_u32 v8, v73, 10, 11
	v_bitop3_b32 v7, v7, v8, 28 bitop3:0x6c
	v_lshl_add_u32 v7, v7, 2, v40
	ds_add_u32 v7, v186
	s_or_b64 exec, exec, s[0:1]
	v_lshrrev_b32_e32 v7, 21, v72
	v_cmp_eq_u32_e32 vcc, v7, v6
	s_and_saveexec_b64 s[0:1], vcc
	v_lshrrev_b32_e32 v7, 13, v72
	v_bfe_u32 v8, v72, 10, 11
	v_bitop3_b32 v7, v7, v8, 28 bitop3:0x6c
	v_lshl_add_u32 v7, v7, 2, v40
	ds_add_u32 v7, v186
	s_or_b64 exec, exec, s[0:1]
	v_lshrrev_b32_e32 v7, 21, v71
	v_cmp_eq_u32_e32 vcc, v7, v6
	s_and_saveexec_b64 s[0:1], vcc
	v_lshrrev_b32_e32 v7, 13, v71
	v_bfe_u32 v8, v71, 10, 11
	v_bitop3_b32 v7, v7, v8, 28 bitop3:0x6c
	v_lshl_add_u32 v7, v7, 2, v40
	ds_add_u32 v7, v186
	s_or_b64 exec, exec, s[0:1]
	v_lshrrev_b32_e32 v7, 21, v70
	v_cmp_eq_u32_e32 vcc, v7, v6
	s_and_saveexec_b64 s[0:1], vcc
	v_lshrrev_b32_e32 v7, 13, v70
	v_bfe_u32 v8, v70, 10, 11
	v_bitop3_b32 v7, v7, v8, 28 bitop3:0x6c
	v_lshl_add_u32 v7, v7, 2, v40
	ds_add_u32 v7, v186
	s_or_b64 exec, exec, s[0:1]
.Ll2s_28:
	s_cmpk_lt_i32 s77, 0xc8
	s_cbranch_scc0 .LBB0_1529

.LBB0_1680:
	v_xor_b32_e32 v7, v12, v65
	v_xor_b32_e32 v8, v12, v64
	v_xor_b32_e32 v9, v12, v63
	v_xor_b32_e32 v10, v12, v62
	v_min3_u32 v7, v7, v8, v9
	v_min_u32_e32 v7, v7, v10
	v_cmp_gt_u32_e32 vcc, 0x200000, v7
	s_cbranch_vccz .Ll2s_29
	v_lshrrev_b32_e32 v7, 21, v65
	s_waitcnt lgkmcnt(0)
	v_cmp_eq_u32_e32 vcc, v7, v6
	s_and_saveexec_b64 s[0:1], vcc
	v_lshrrev_b32_e32 v7, 13, v65
	v_bfe_u32 v8, v65, 10, 11
	v_bitop3_b32 v7, v7, v8, 28 bitop3:0x6c
	v_lshl_add_u32 v7, v7, 2, v40
	ds_add_u32 v7, v186
	s_or_b64 exec, exec, s[0:1]
	v_lshrrev_b32_e32 v7, 21, v64
	v_cmp_eq_u32_e32 vcc, v7, v6
	s_and_saveexec_b64 s[0:1], vcc
	v_lshrrev_b32_e32 v7, 13, v64
	v_bfe_u32 v8, v64, 10, 11
	v_bitop3_b32 v7, v7, v8, 28 bitop3:0x6c
	v_lshl_add_u32 v7, v7, 2, v40
	ds_add_u32 v7, v186
	s_or_b64 exec, exec, s[0:1]
	v_lshrrev_b32_e32 v7, 21, v63
	v_cmp_eq_u32_e32 vcc, v7, v6
	s_and_saveexec_b64 s[0:1], vcc
	v_lshrrev_b32_e32 v7, 13, v63
	v_bfe_u32 v8, v63, 10, 11
	v_bitop3_b32 v7, v7, v8, 28 bitop3:0x6c
	v_lshl_add_u32 v7, v7, 2, v40
	ds_add_u32 v7, v186
	s_or_b64 exec, exec, s[0:1]
	v_lshrrev_b32_e32 v7, 21, v62
	v_cmp_eq_u32_e32 vcc, v7, v6
	s_and_saveexec_b64 s[0:1], vcc
	v_lshrrev_b32_e32 v7, 13, v62
	v_bfe_u32 v8, v62, 10, 11
	v_bitop3_b32 v7, v7, v8, 28 bitop3:0x6c
	v_lshl_add_u32 v7, v7, 2, v40
	ds_add_u32 v7, v186
	s_or_b64 exec, exec, s[0:1]
.Ll2s_29:
	s_cmpk_lt_i32 s77, 0xd8
	s_cbranch_scc0 .LBB0_1539

.LBB0_1690:
	v_xor_b32_e32 v7, v12, v57
	v_xor_b32_e32 v8, v12, v56
	v_xor_b32_e32 v9, v12, v55
	v_xor_b32_e32 v10, v12, v54
	v_min3_u32 v7, v7, v8, v9
	v_min_u32_e32 v7, v7, v10
	v_cmp_gt_u32_e32 vcc, 0x200000, v7
	s_cbranch_vccz .Ll2s_30
	v_lshrrev_b32_e32 v7, 21, v57
	s_waitcnt lgkmcnt(0)
	v_cmp_eq_u32_e32 vcc, v7, v6
	s_and_saveexec_b64 s[0:1], vcc
	v_lshrrev_b32_e32 v7, 13, v57
	v_bfe_u32 v8, v57, 10, 11
	v_bitop3_b32 v7, v7, v8, 28 bitop3:0x6c
	v_lshl_add_u32 v7, v7, 2, v40
	ds_add_u32 v7, v186
	s_or_b64 exec, exec, s[0:1]
	v_lshrrev_b32_e32 v7, 21, v56
	v_cmp_eq_u32_e32 vcc, v7, v6
	s_and_saveexec_b64 s[0:1], vcc
	v_lshrrev_b32_e32 v7, 13, v56
	v_bfe_u32 v8, v56, 10, 11
	v_bitop3_b32 v7, v7, v8, 28 bitop3:0x6c
	v_lshl_add_u32 v7, v7, 2, v40
	ds_add_u32 v7, v186
	s_or_b64 exec, exec, s[0:1]
	v_lshrrev_b32_e32 v7, 21, v55
	v_cmp_eq_u32_e32 vcc, v7, v6
	s_and_saveexec_b64 s[0:1], vcc
	v_lshrrev_b32_e32 v7, 13, v55
	v_bfe_u32 v8, v55, 10, 11
	v_bitop3_b32 v7, v7, v8, 28 bitop3:0x6c
	v_lshl_add_u32 v7, v7, 2, v40
	ds_add_u32 v7, v186
	s_or_b64 exec, exec, s[0:1]
	v_lshrrev_b32_e32 v7, 21, v54
	v_cmp_eq_u32_e32 vcc, v7, v6
	s_and_saveexec_b64 s[0:1], vcc
	v_lshrrev_b32_e32 v7, 13, v54
	v_bfe_u32 v8, v54, 10, 11
	v_bitop3_b32 v7, v7, v8, 28 bitop3:0x6c
	v_lshl_add_u32 v7, v7, 2, v40
	ds_add_u32 v7, v186
	s_or_b64 exec, exec, s[0:1]
.Ll2s_30:
	s_cmpk_lt_i32 s77, 0xe8
	s_cbranch_scc0 .LBB0_1549

.LBB0_1700:
	v_xor_b32_e32 v7, v12, v49
	v_xor_b32_e32 v8, v12, v48
	v_xor_b32_e32 v9, v12, v47
	v_xor_b32_e32 v10, v12, v46
	v_min3_u32 v7, v7, v8, v9
	v_min_u32_e32 v7, v7, v10
	v_cmp_gt_u32_e32 vcc, 0x200000, v7
	s_cbranch_vccz .Ll2s_31
	v_lshrrev_b32_e32 v7, 21, v49
	s_waitcnt lgkmcnt(0)
	v_cmp_eq_u32_e32 vcc, v7, v6
	s_and_saveexec_b64 s[0:1], vcc
	v_lshrrev_b32_e32 v7, 13, v49
	v_bfe_u32 v8, v49, 10, 11
	v_bitop3_b32 v7, v7, v8, 28 bitop3:0x6c
	v_lshl_add_u32 v7, v7, 2, v40
	ds_add_u32 v7, v186
	s_or_b64 exec, exec, s[0:1]
	v_lshrrev_b32_e32 v7, 21, v48
	v_cmp_eq_u32_e32 vcc, v7, v6
	s_and_saveexec_b64 s[0:1], vcc
	v_lshrrev_b32_e32 v7, 13, v48
	v_bfe_u32 v8, v48, 10, 11
	v_bitop3_b32 v7, v7, v8, 28 bitop3:0x6c
	v_lshl_add_u32 v7, v7, 2, v40
	ds_add_u32 v7, v186
	s_or_b64 exec, exec, s[0:1]
	v_lshrrev_b32_e32 v7, 21, v47
	v_cmp_eq_u32_e32 vcc, v7, v6
	s_and_saveexec_b64 s[0:1], vcc
	v_lshrrev_b32_e32 v7, 13, v47
	v_bfe_u32 v8, v47, 10, 11
	v_bitop3_b32 v7, v7, v8, 28 bitop3:0x6c
	v_lshl_add_u32 v7, v7, 2, v40
	ds_add_u32 v7, v186
	s_or_b64 exec, exec, s[0:1]
	v_lshrrev_b32_e32 v7, 21, v46
	v_cmp_eq_u32_e32 vcc, v7, v6
	s_and_saveexec_b64 s[0:1], vcc
	v_lshrrev_b32_e32 v7, 13, v46
	v_bfe_u32 v8, v46, 10, 11
	v_bitop3_b32 v7, v7, v8, 28 bitop3:0x6c
	v_lshl_add_u32 v7, v7, 2, v40
	ds_add_u32 v7, v186
	s_or_b64 exec, exec, s[0:1]
.Ll2s_31:
	s_cmpk_lt_i32 s77, 0xf8
	s_cbranch_scc1 .LBB0_1717
.LBB0_1709:
	v_xor_b32_e32 v7, v12, v45
	v_xor_b32_e32 v8, v12, v44
	v_xor_b32_e32 v9, v12, v43
	v_xor_b32_e32 v10, v12, v42
	v_min3_u32 v7, v7, v8, v9
	v_min_u32_e32 v7, v7, v10
	v_cmp_gt_u32_e32 vcc, 0x200000, v7
	s_cbranch_vccz .LBB0_1717
	v_lshrrev_b32_e32 v7, 21, v45
	s_waitcnt lgkmcnt(0)
	v_cmp_eq_u32_e32 vcc, v7, v6
	s_and_saveexec_b64 s[0:1], vcc
	v_lshrrev_b32_e32 v7, 13, v45
	v_bfe_u32 v8, v45, 10, 11
	v_bitop3_b32 v7, v7, v8, 28 bitop3:0x6c
	v_lshl_add_u32 v7, v7, 2, v40
	ds_add_u32 v7, v186
	s_or_b64 exec, exec, s[0:1]
	v_lshrrev_b32_e32 v7, 21, v44
	v_cmp_eq_u32_e32 vcc, v7, v6
	s_and_saveexec_b64 s[0:1], vcc
	v_lshrrev_b32_e32 v7, 13, v44
	v_bfe_u32 v8, v44, 10, 11
	v_bitop3_b32 v7, v7, v8, 28 bitop3:0x6c
	v_lshl_add_u32 v7, v7, 2, v40
	ds_add_u32 v7, v186
	s_or_b64 exec, exec, s[0:1]
	v_lshrrev_b32_e32 v7, 21, v43
	v_cmp_eq_u32_e32 vcc, v7, v6
	s_and_saveexec_b64 s[0:1], vcc
	v_lshrrev_b32_e32 v7, 13, v43
	v_bfe_u32 v8, v43, 10, 11
	v_bitop3_b32 v7, v7, v8, 28 bitop3:0x6c
	v_lshl_add_u32 v7, v7, 2, v40
	ds_add_u32 v7, v186
	s_or_b64 exec, exec, s[0:1]
	v_lshrrev_b32_e32 v7, 21, v42
	v_cmp_eq_u32_e32 vcc, v7, v6
	s_and_b64 exec, exec, vcc
	v_lshrrev_b32_e32 v6, 13, v42
	v_bfe_u32 v7, v42, 10, 11
	v_bitop3_b32 v6, v6, v7, 28 bitop3:0x6c
	v_lshl_add_u32 v6, v6, 2, v40
	ds_add_u32 v6, v186
